# P10 tail waves pre-touch the fp16 residual HB into the memory-side cache for the P11 epilogue (on v157)
# speedup vs baseline: 1.0053x; 1.0031x over previous
.Lmy_td10:
	s_waitcnt vmcnt(0)
	s_mov_b64 s[6:7], exec
	s_mov_b64 exec, 1
	v_mov_b32_e32 v2, 0x37100
	v_mov_b32_e32 v3, 1
	global_atomic_add v2, v3, s[50:51]
	s_mov_b64 exec, s[6:7]
	v_readlane_b32 s10, v254, 10
	s_sub_u32 s11, s2, 0x80
	s_lshl_b32 s11, s11, 3
	s_add_u32 s10, s10, s11
	s_and_b32 s10, s10, 0x3ff
	s_lshl_b32 s10, s10, 15
	s_add_u32 s10, s10, 0x1c400000
	s_add_u32 s12, s50, s10
	s_addc_u32 s13, s51, 0
	v_and_b32_e32 v2, 63, v0
	v_lshlrev_b32_e32 v2, 6, v2
	global_load_dword v4, v2, s[12:13]
	v_add_u32_e32 v2, 0x1000, v2
	global_load_dword v5, v2, s[12:13]
	v_add_u32_e32 v2, 0x1000, v2
	global_load_dword v6, v2, s[12:13]
	v_add_u32_e32 v2, 0x1000, v2
	global_load_dword v7, v2, s[12:13]
	v_add_u32_e32 v2, 0x1000, v2
	global_load_dword v8, v2, s[12:13]
	v_add_u32_e32 v2, 0x1000, v2
	global_load_dword v9, v2, s[12:13]
	v_add_u32_e32 v2, 0x1000, v2
	global_load_dword v10, v2, s[12:13]
	v_add_u32_e32 v2, 0x1000, v2
	global_load_dword v11, v2, s[12:13]
	s_waitcnt vmcnt(0)
